# attention tiles: cross-half exchange select reduced from cmp+2 cndmask to one cndmask (bit-identical)
# baseline (speedup 1.0000x reference)
; #define LAS __attribute__((address_space(3)))
; __device__ __forceinline__ unsigned pk_bf16(float lo, float hi) { return pg8::cvt_pk_bf16(lo, hi); }
; #define ATT_SB() do {} while (0)
; template <bool DO_PV> ...
;     f32x16 p[2];
; #pragma unroll
;     for (int r = 0; r < 16; ++r) { p[0][r] = 0.f; p[1][r] = 0.f; }
;     bf16x8 vf[16];
;     if (DO_PV) { ATT_VLD(0); ATT_VLD(1); ATT_VLD(2); ATT_VLD(3); }
;     {
;         bf16x8 ka[8], kc[8];
; #pragma unroll
;         for (int d0 = 0; d0 < 8; ++d0) { ka[d0] = *(const LAS bf16x8*)(kb + koff[d0]); kc[d0] = *(const LAS bf16x8*)(kb + 8192 + koff[d0]); }
;         ATT_SB();
; #pragma unroll
;         for (int d0 = 0; d0 < 8; ++d0) {
;             p[0] = __builtin_amdgcn_mfma_f32_32x32x16_bf16(ka[d0], qf[d0], p[0], 0, 0, 0);
;             p[1] = __builtin_amdgcn_mfma_f32_32x32x16_bf16(kc[d0], qf[d0], p[1], 0, 0, 0);
;         }
;     }
;     ATT_SB();
;     const bool need_mask = (k0 + 63 >= qw0);
;     float L[8], T[8];
;     ATT_PV(0); ATT_EXP8(0); ATT_SB();
;     ATT_PV(1); ATT_EXP8(1); ATT_SB();
;     ATT_PV(2); ATT_EXP8(2); ATT_SB();
;     ATT_PV(3); ATT_EXP8(3); ATT_SB();
;     if (need_mask) {
; #pragma unroll
;         for (int ph = 0; ph < 2; ++ph)
; #pragma unroll
;             for (int r = 0; r < 16; ++r) { const int key = k0 + 32 * ph + crow(r, hi); if (key >= qabs) p[ph][r] = 0.f; }
;     }
;     ATT_SB();
;     ATT_PV(4); ATT_LBLK(0); ATT_LBLK(1); ATT_SB();
;     ATT_PV(5); ATT_LBLK(2); ATT_LBLK(3); ATT_SB();
;     ATT_PV(6); ATT_LBLK(4); ATT_LBLK(5); ATT_SB();
;     ATT_PV(7); ATT_LBLK(6); ATT_LBLK(7); ATT_SB();
;     float run = carry;
;     ATT_PV(8); ATT_XCH(0); ATT_XCH(1); ATT_SB();
;     ATT_PV(9); ATT_XCH(2); ATT_XCH(3); ATT_SB();
;     ATT_PV(10); ATT_XCH(4); ATT_XCH(5); ATT_SB();
;     ATT_PV(11); ATT_XCH(6); ATT_XCH(7); ATT_SB();
;     carry = run;
;     ATT_PV(12); ATT_WGT(0); ATT_WGT(1); ATT_SB();
;     ATT_PV(13); ATT_WGT(2); ATT_WGT(3); ATT_SB();
;     ATT_PV(14); ATT_WGT(4); ATT_WGT(5); ATT_SB();
;     ATT_PV(15); ATT_WGT(6); ATT_WGT(7); ATT_SB();
; #pragma unroll
;     for (int s = 0; s < 4; ++s) { const int ph = s >> 1, rb = 8 * (s & 1);
;         u32x4 w; w.x = pk_bf16(p[ph][rb], p[ph][rb + 1]); w.y = pk_bf16(p[ph][rb + 2], p[ph][rb + 3]); w.z = pk_bf16(p[ph][rb + 4], p[ph][rb + 5]); w.w = pk_bf16(p[ph][rb + 6], p[ph][rb + 7]);
;         pa[s] = __builtin_bit_cast(bf16x8, w); }
.LBB0_602:
	v_pk_add_f32 v[78:79], v[76:77], 1.0 op_sel_hi:[1,0]
	v_pk_add_f32 v[170:171], v[74:75], 1.0 op_sel_hi:[1,0]
	v_pk_add_f32 v[174:175], v[70:71], 1.0 op_sel_hi:[1,0]
	v_pk_mul_f32 v[172:173], v[78:79], v[170:171]
	v_pk_add_f32 v[196:197], v[66:67], 1.0 op_sel_hi:[1,0]
	v_mul_f32_e32 v159, v172, v173
	v_pk_add_f32 v[172:173], v[72:73], 1.0 op_sel_hi:[1,0]
	v_pk_add_f32 v[200:201], v[64:65], 1.0 op_sel_hi:[1,0]
	v_pk_mul_f32 v[176:177], v[172:173], v[174:175]
	v_pk_add_f32 v[204:205], v[90:91], 1.0 op_sel_hi:[1,0]
	v_mul_f32_e32 v169, v176, v177
	v_pk_add_f32 v[176:177], v[68:69], 1.0 op_sel_hi:[1,0]
	v_log_f32_e32 v159, v159
	v_pk_mul_f32 v[198:199], v[176:177], v[196:197]
	v_pk_add_f32 v[208:209], v[86:87], 1.0 op_sel_hi:[1,0]
	v_mul_f32_e32 v171, v198, v199
	v_pk_add_f32 v[198:199], v[94:95], 1.0 op_sel_hi:[1,0]
	v_pk_add_f32 v[212:213], v[82:83], 1.0 op_sel_hi:[1,0]
	v_pk_mul_f32 v[202:203], v[198:199], v[200:201]
	v_log_f32_e32 v169, v169
	v_mul_f32_e32 v175, v202, v203
	v_pk_add_f32 v[202:203], v[92:93], 1.0 op_sel_hi:[1,0]
	v_pk_add_f32 v[216:217], v[80:81], 1.0 op_sel_hi:[1,0]
	v_pk_mul_f32 v[206:207], v[202:203], v[204:205]
	v_log_f32_e32 v171, v171
	v_mul_f32_e32 v194, v206, v207
	v_pk_add_f32 v[206:207], v[88:89], 1.0 op_sel_hi:[1,0]
	v_log_f32_e32 v175, v175
	v_pk_mul_f32 v[210:211], v[206:207], v[208:209]
	v_mov_b32_e32 v209, v159
	v_mul_f32_e32 v197, v210, v211
	v_pk_add_f32 v[210:211], v[84:85], 1.0 op_sel_hi:[1,0]
	v_mov_b32_e32 v221, v175
	v_pk_mul_f32 v[214:215], v[210:211], v[212:213]
	v_mov_b32_e32 v213, v159
	s_nop 1
	v_permlane32_swap_b32_e32 v209, v213
	v_mul_f32_e32 v201, v214, v215
	v_pk_add_f32 v[214:215], v[160:161], 1.0 op_sel_hi:[1,0]
	v_pk_mul_f32 v[218:219], v[214:215], v[216:217]
	v_log_f32_e32 v194, v194
	v_cndmask_b32_e64 v217, 0, v213, s[0:1]
	v_add_f32_e32 v217, v158, v217
	v_mul_f32_e32 v205, v218, v219
	v_add_f32_e32 v217, v159, v217
	v_mov_b32_e32 v159, v169
	v_mov_b32_e32 v219, v169
	s_nop 1
	v_permlane32_swap_b32_e32 v159, v219
	v_add_f32_e32 v218, v209, v213
	v_mov_b32_e32 v213, v171
	v_log_f32_e32 v197, v197
	v_cndmask_b32_e64 v209, 0, v219, s[0:1]
	v_pk_add_f32 v[218:219], v[158:159], v[218:219]
	v_mov_b32_e32 v159, v171
	s_nop 1
	v_permlane32_swap_b32_e32 v159, v213
	v_add_f32_e32 v209, v218, v209
	v_pk_add_f32 v[218:219], v[218:219], v[218:219] op_sel:[0,1] op_sel_hi:[1,0]
	v_add_f32_e32 v220, v159, v213
	v_log_f32_e32 v201, v201
	v_cndmask_b32_e64 v219, 0, v213, s[0:1]
	v_add_f32_e32 v222, v218, v219
	v_mov_b32_e32 v219, v175
	s_nop 1
	v_permlane32_swap_b32_e32 v219, v221
	v_log_f32_e32 v205, v205
	v_exp_f32_e64 v217, -v217
	v_cndmask_b32_e64 v159, 0, v221, s[0:1]
	v_pk_add_f32 v[218:219], v[218:219], v[220:221]
	v_mov_b32_e32 v221, v197
	v_add_f32_e32 v213, v218, v159
	v_pk_add_f32 v[218:219], v[218:219], v[218:219] op_sel:[0,1] op_sel_hi:[1,0]
	v_mov_b32_e32 v159, v194
	v_mov_b32_e32 v219, v194
	s_nop 1
	v_permlane32_swap_b32_e32 v159, v219
	s_mov_b64 s[4:5], 0
	s_nop 0
	v_cndmask_b32_e64 v220, 0, v219, s[0:1]
	v_add_f32_e32 v223, v218, v220
	v_add_f32_e32 v220, v159, v219
	v_mov_b32_e32 v219, v197
	s_nop 1
	v_permlane32_swap_b32_e32 v219, v221
	s_nop 1
	v_cndmask_b32_e64 v159, 0, v221, s[0:1]
	v_pk_add_f32 v[218:219], v[218:219], v[220:221]
	v_mov_b32_e32 v221, v205
	v_add_f32_e32 v224, v218, v159
	v_pk_add_f32 v[218:219], v[218:219], v[218:219] op_sel:[0,1] op_sel_hi:[1,0]
	v_mov_b32_e32 v159, v201
	v_mov_b32_e32 v219, v201
	s_nop 1
	v_permlane32_swap_b32_e32 v159, v219
	s_nop 1
	v_cndmask_b32_e64 v220, 0, v219, s[0:1]
	v_add_f32_e32 v225, v218, v220
	v_add_f32_e32 v220, v159, v219
	v_mov_b32_e32 v219, v205
	s_nop 1
	v_permlane32_swap_b32_e32 v219, v221
	s_nop 1
	v_cndmask_b32_e64 v159, 0, v221, s[0:1]
	v_pk_add_f32 v[218:219], v[218:219], v[220:221]
	s_nop 0
	v_add_f32_e32 v220, v218, v159
	v_add_f32_e32 v159, v218, v219
	v_mul_f32_e32 v218, v74, v217
	v_mul_f32_e32 v74, v170, v217
	v_mul_f32_e32 v170, v76, v74
	v_mul_f32_e32 v74, v78, v74
	v_mul_f32_e32 v217, v77, v74
	v_mul_f32_e32 v74, v79, v74
	v_mul_f32_e32 v79, v75, v74
	v_add_f32_e32 v74, v169, v209
	v_exp_f32_e64 v74, -v74
	v_add_f32_e32 v75, v171, v222
	v_add_f32_e32 v76, v194, v223
	v_add_f32_e32 v77, v201, v225
	v_mul_f32_e32 v78, v70, v74
	v_mul_f32_e32 v70, v174, v74
	v_mul_f32_e32 v169, v72, v70
	v_exp_f32_e64 v72, -v75
	v_mul_f32_e32 v70, v172, v70
	v_mul_f32_e32 v171, v73, v70
	v_mul_f32_e32 v70, v173, v70
	v_mul_f32_e32 v74, v66, v72
	v_mul_f32_e32 v66, v196, v72
	v_mul_f32_e32 v75, v68, v66
	v_add_f32_e32 v68, v175, v213
	v_exp_f32_e64 v68, -v68
	v_mul_f32_e32 v66, v176, v66
	v_mul_f32_e32 v173, v69, v66
	v_mul_f32_e32 v66, v177, v66
	v_mul_f32_e32 v174, v67, v66
	v_mul_f32_e32 v72, v64, v68
	v_mul_f32_e32 v64, v200, v68
	v_exp_f32_e64 v66, -v76
	v_mul_f32_e32 v73, v94, v64
	v_mul_f32_e32 v64, v198, v64
	v_mul_f32_e32 v172, v71, v70
	v_add_f32_e32 v70, v197, v224
	v_mul_f32_e32 v76, v95, v64
	v_mul_f32_e32 v64, v199, v64
	v_mul_f32_e32 v94, v65, v64
	v_exp_f32_e64 v65, -v70
	v_mul_f32_e32 v64, v204, v66
	v_mul_f32_e32 v71, v90, v66
	v_mul_f32_e32 v90, v92, v64
	v_mul_f32_e32 v64, v202, v64
	v_mul_f32_e32 v92, v93, v64
	v_mul_f32_e32 v64, v203, v64
	v_mul_f32_e32 v91, v91, v64
	v_mul_f32_e32 v68, v86, v65
	v_mul_f32_e32 v64, v208, v65
	v_exp_f32_e64 v65, -v77
	v_mul_f32_e32 v69, v88, v64
	v_mul_f32_e32 v64, v206, v64
	v_mul_f32_e32 v70, v89, v64
	v_mul_f32_e32 v64, v207, v64
	v_mul_f32_e32 v77, v87, v64
	v_mul_f32_e32 v66, v82, v65
	v_mul_f32_e32 v64, v212, v65
	v_add_f32_e32 v65, v205, v220
	v_exp_f32_e64 v65, -v65
	v_mul_f32_e32 v67, v84, v64
	v_mul_f32_e32 v64, v210, v64
	v_mul_f32_e32 v82, v85, v64
	v_mul_f32_e32 v64, v211, v64
	v_mul_f32_e32 v83, v83, v64
	v_mul_f32_e32 v64, v80, v65
	v_mul_f32_e32 v65, v216, v65
	v_mul_f32_e32 v80, v160, v65
	v_mul_f32_e32 v65, v214, v65
	v_mul_f32_e32 v84, v161, v65
	v_mul_f32_e32 v65, v215, v65
	v_mul_f32_e32 v65, v81, v65
	v_cvt_pk_bf16_f32 v64, v64, v80
	v_cvt_pk_bf16_f32 v65, v84, v65
	v_cvt_pk_bf16_f32 v66, v66, v67
	v_cvt_pk_bf16_f32 v67, v82, v83
	v_cvt_pk_bf16_f32 v68, v68, v69
	v_cvt_pk_bf16_f32 v69, v70, v77
	v_cvt_pk_bf16_f32 v70, v71, v90
	v_cvt_pk_bf16_f32 v71, v92, v91
	v_cvt_pk_bf16_f32 v72, v72, v73
	v_cvt_pk_bf16_f32 v73, v76, v94
	v_cvt_pk_bf16_f32 v74, v74, v75
	v_cvt_pk_bf16_f32 v75, v173, v174
	v_cvt_pk_bf16_f32 v76, v78, v169
	v_cvt_pk_bf16_f32 v77, v171, v172
	v_cvt_pk_bf16_f32 v78, v218, v170
	v_cvt_pk_bf16_f32 v79, v217, v79

; #define LAS __attribute__((address_space(3)))
; __device__ __forceinline__ int crow(int r, int hi) { return (r & 3) + 8 * (r >> 2) + 4 * hi; }
; #define ATT_SB() do {} while (0)
; #define ATT_SB() do {} while (0)
; #define ATT_SB() __builtin_amdgcn_sched_barrier(0)
; #define ATT_VLD(f) do { const int c_ = (f) >> 2, s_ = (f) & 3; const s16x4 lo_ = vtr(vbp + 4096 * s_ + vbase[0] + vcq[c_]); const s16x4 hh_ = vtr(vbp + 4096 * s_ + vbase[1] + vcq[c_]); \
;         vf[f] = (bf16x8){lo_[0], lo_[1], lo_[2], lo_[3], hh_[0], hh_[1], hh_[2], hh_[3]}; } while (0)
; #define ATT_PV(f) do { if (DO_PV) { o[(f) >> 2] = __builtin_amdgcn_mfma_f32_32x32x16_bf16(pa[(f) & 3], vf[f], o[(f) >> 2], 0, 0, 0); if ((f) + 4 < 16) ATT_VLD((f) + 4); } } while (0)
; template <bool DO_PV> ...
;     f32x16 p[2];
; #pragma unroll
;     for (int r = 0; r < 16; ++r) { p[0][r] = 0.f; p[1][r] = 0.f; }
;     bf16x8 vf[16];
;     if (DO_PV) { ATT_VLD(0); ATT_VLD(1); ATT_VLD(2); ATT_VLD(3); }
;     {
;         bf16x8 ka[8], kc[8];
; #pragma unroll
;         for (int d0 = 0; d0 < 8; ++d0) { ka[d0] = *(const LAS bf16x8*)(kb + koff[d0]); kc[d0] = *(const LAS bf16x8*)(kb + 8192 + koff[d0]); }
;         ATT_SB();
; #pragma unroll
;         for (int d0 = 0; d0 < 8; ++d0) {
;             p[0] = __builtin_amdgcn_mfma_f32_32x32x16_bf16(ka[d0], qf[d0], p[0], 0, 0, 0);
;             p[1] = __builtin_amdgcn_mfma_f32_32x32x16_bf16(kc[d0], qf[d0], p[1], 0, 0, 0);
;         }
;     }
;     ATT_SB();
;     const bool need_mask = (k0 + 63 >= qw0);
;     float L[8], T[8];
;     ATT_PV(0); ATT_EXP8(0); ATT_SB();
;     ATT_PV(1); ATT_EXP8(1); ATT_SB();
;     ATT_PV(2); ATT_EXP8(2); ATT_SB();
;     ATT_PV(3); ATT_EXP8(3); ATT_SB();
;     if (need_mask) {
; #pragma unroll
;         for (int ph = 0; ph < 2; ++ph)
; #pragma unroll
;             for (int r = 0; r < 16; ++r) { const int key = k0 + 32 * ph + crow(r, hi); if (key >= qabs) p[ph][r] = 0.f; }
;     }
;     ATT_SB();
;     ATT_PV(4); ATT_LBLK(0); ATT_LBLK(1); ATT_SB();
;     ATT_PV(5); ATT_LBLK(2); ATT_LBLK(3); ATT_SB();
;     ATT_PV(6); ATT_LBLK(4); ATT_LBLK(5); ATT_SB();
;     ATT_PV(7); ATT_LBLK(6); ATT_LBLK(7); ATT_SB();
;     float run = carry;
;     ATT_PV(8); ATT_XCH(0); ATT_XCH(1); ATT_SB();
;     ATT_PV(9); ATT_XCH(2); ATT_XCH(3); ATT_SB();
;     ATT_PV(10); ATT_XCH(4); ATT_XCH(5); ATT_SB();
;     ATT_PV(11); ATT_XCH(6); ATT_XCH(7); ATT_SB();
.LBB0_606:
	s_waitcnt lgkmcnt(0)
	v_mfma_f32_32x32x16_bf16 v[48:63], v[140:143], v[84:87], v[48:63]
	v_add_f32_e64 v196, v76, 1.0
	v_add_f32_e64 v197, v77, 1.0
	v_add_f32_e64 v198, v74, 1.0
	v_add_f32_e64 v199, v75, 1.0
	v_add_f32_e64 v86, v176, 1.0
	v_add_f32_e64 v87, v177, 1.0
	v_pk_mul_f32 v[78:79], v[196:197], v[198:199]
	v_pk_add_f32 v[200:201], v[72:73], 1.0 op_sel_hi:[1,0]
	v_mul_f32_e32 v78, v78, v79
	v_log_f32_e32 v199, v78
	v_mfma_f32_32x32x16_bf16 v[48:63], v[136:139], v[80:83], v[48:63]
	v_mul_f32_e64 v78, v86, v200
	v_mul_f32_e64 v79, v87, v201
	v_add_f32_e64 v202, v174, 1.0
	v_add_f32_e64 v203, v175, 1.0
	v_mul_f32_e32 v78, v78, v79
	v_pk_add_f32 v[204:205], v[172:173], 1.0 op_sel_hi:[1,0]
	v_pk_add_f32 v[210:211], v[92:93], 1.0 op_sel_hi:[1,0]
	v_pk_add_f32 v[212:213], v[90:91], 1.0 op_sel_hi:[1,0]
	v_log_f32_e32 v201, v78
	v_mfma_f32_32x32x16_bf16 v[48:63], v[132:135], v[68:71], v[48:63]
	v_mul_f32_e64 v78, v202, v204
	v_mul_f32_e64 v79, v203, v205
	v_mul_f32_e64 v68, v210, v212
	v_mul_f32_e64 v69, v211, v213
	v_mul_f32_e32 v78, v78, v79
	v_pk_add_f32 v[206:207], v[170:171], 1.0 op_sel_hi:[1,0]
	v_pk_add_f32 v[208:209], v[94:95], 1.0 op_sel_hi:[1,0]
	v_mul_f32_e32 v68, v68, v69
	v_pk_add_f32 v[214:215], v[168:169], 1.0 op_sel_hi:[1,0]
	v_pk_add_f32 v[216:217], v[88:89], 1.0 op_sel_hi:[1,0]
	v_log_f32_e32 v205, v78
	v_pk_mul_f32 v[78:79], v[206:207], v[208:209]
	v_log_f32_e32 v213, v68
	v_pk_mul_f32 v[68:69], v[214:215], v[216:217]
	v_add_u32_e32 v149, v194, v192
	v_mul_f32_e32 v78, v78, v79
	v_mul_f32_e32 v68, v68, v69
	v_add_u32_e32 v218, v159, v192
	v_log_f32_e32 v209, v78
	v_log_f32_e32 v217, v68
	v_mfma_f32_32x32x16_bf16 v[48:63], v[128:131], v[64:67], v[48:63]
	ds_read_b64_tr_b16 v[64:65], v149 offset:32768
	ds_read_b64_tr_b16 v[68:69], v149 offset:36864
	ds_read_b64_tr_b16 v[78:79], v149 offset:40960
	ds_read_b64_tr_b16 v[82:83], v149 offset:45056
	ds_read_b64_tr_b16 v[66:67], v218 offset:34816
	ds_read_b64_tr_b16 v[70:71], v218 offset:38912
	ds_read_b64_tr_b16 v[80:81], v218 offset:43008
	ds_read_b64_tr_b16 v[84:85], v218 offset:47104
	v_pk_add_f32 v[218:219], v[166:167], 1.0 op_sel_hi:[1,0]
	v_pk_add_f32 v[220:221], v[164:165], 1.0 op_sel_hi:[1,0]
	v_pk_add_f32 v[224:225], v[160:161], 1.0 op_sel_hi:[1,0]
	v_pk_mul_f32 v[222:223], v[218:219], v[220:221]
	v_add_u32_e32 v194, v194, v193
	v_mul_f32_e32 v149, v222, v223
	s_waitcnt lgkmcnt(0)
	v_mfma_f32_32x32x16_bf16 v[0:15], v[140:143], v[64:67], v[0:15]
	v_mov_b32_e32 v64, v199
	v_mov_b32_e32 v65, v199
	s_nop 1
	v_permlane32_swap_b32_e32 v64, v65
	v_add_f32_e64 v222, v162, 1.0
	v_add_f32_e64 v223, v163, 1.0
	v_pk_mul_f32 v[226:227], v[222:223], v[224:225]
	v_add_u32_e32 v225, v159, v193
	v_cndmask_b32_e64 v66, 0, v65, s[0:1]
	v_add_f32_e32 v64, v64, v65
	v_mov_b32_e32 v159, v201
	v_mov_b32_e32 v65, v201
	s_nop 1
	v_permlane32_swap_b32_e32 v159, v65
	v_add_f32_e32 v66, v158, v66
	v_add_f32_e32 v199, v199, v66
	v_mfma_f32_32x32x16_bf16 v[0:15], v[136:139], v[68:71], v[0:15]
	v_cndmask_b32_e64 v66, 0, v65, s[0:1]
	v_add_f32_e64 v64, v158, v64
	v_add_f32_e64 v65, v159, v65
	v_exp_f32_e64 v199, -v199
	v_add_f32_e32 v228, v64, v66
	v_pk_add_f32 v[64:65], v[64:65], v[64:65] op_sel:[0,1] op_sel_hi:[1,0]
	v_mov_b32_e32 v66, v205
	v_mov_b32_e32 v65, v205
	s_nop 1
	v_permlane32_swap_b32_e32 v65, v66
	v_mfma_f32_32x32x16_bf16 v[0:15], v[132:135], v[78:81], v[0:15]
	v_log_f32_e32 v149, v149
	v_cndmask_b32_e64 v67, 0, v66, s[0:1]
	v_add_f32_e32 v229, v64, v67
	v_add_f32_e32 v66, v65, v66
	v_mov_b32_e32 v65, v209
	v_mov_b32_e32 v67, v209
	s_nop 1
	v_permlane32_swap_b32_e32 v65, v67
	v_mfma_f32_32x32x16_bf16 v[0:15], v[128:131], v[82:85], v[0:15]
	v_mul_f32_e32 v221, v226, v227
	v_cndmask_b32_e64 v68, 0, v67, s[0:1]
	v_add_f32_e64 v64, v64, v66
	v_add_f32_e64 v65, v65, v67
	v_mov_b32_e32 v66, v213
	v_add_f32_e32 v230, v64, v68
	v_pk_add_f32 v[64:65], v[64:65], v[64:65] op_sel:[0,1] op_sel_hi:[1,0]
	v_log_f32_e32 v221, v221
	v_mov_b32_e32 v65, v213
	s_nop 1
	v_permlane32_swap_b32_e32 v65, v66
	v_mov_b32_e32 v227, v221
	s_nop 0
	v_cndmask_b32_e64 v67, 0, v66, s[0:1]
	v_add_f32_e32 v231, v64, v67
	v_add_f32_e32 v66, v65, v66
	v_mov_b32_e32 v65, v217
	v_mov_b32_e32 v67, v217
	s_nop 1
	v_permlane32_swap_b32_e32 v65, v67
	s_nop 1
	v_cndmask_b32_e64 v68, 0, v67, s[0:1]
	v_pk_add_f32 v[64:65], v[64:65], v[66:67]
	s_nop 0
	v_add_f32_e32 v232, v64, v68
	v_pk_add_f32 v[158:159], v[64:65], v[64:65] op_sel:[0,1] op_sel_hi:[1,0]
	ds_read_b64_tr_b16 v[64:65], v194 offset:32768
	ds_read_b64_tr_b16 v[68:69], v194 offset:36864
	ds_read_b64_tr_b16 v[78:79], v194 offset:40960
	ds_read_b64_tr_b16 v[82:83], v194 offset:45056
	ds_read_b64_tr_b16 v[66:67], v225 offset:34816
	ds_read_b64_tr_b16 v[70:71], v225 offset:38912
	ds_read_b64_tr_b16 v[80:81], v225 offset:43008
	ds_read_b64_tr_b16 v[84:85], v225 offset:47104
	s_waitcnt lgkmcnt(0)
; #define LAS __attribute__((address_space(3)))
; __device__ __forceinline__ unsigned pk_bf16(float lo, float hi) { return pg8::cvt_pk_bf16(lo, hi); }
; #define ATT_SB() do {} while (0)
; template <bool DO_PV> ...
;     f32x16 p[2];
; #pragma unroll
;     for (int r = 0; r < 16; ++r) { p[0][r] = 0.f; p[1][r] = 0.f; }
;     bf16x8 vf[16];
;     if (DO_PV) { ATT_VLD(0); ATT_VLD(1); ATT_VLD(2); ATT_VLD(3); }
;     {
;         bf16x8 ka[8], kc[8];
; #pragma unroll
;         for (int d0 = 0; d0 < 8; ++d0) { ka[d0] = *(const LAS bf16x8*)(kb + koff[d0]); kc[d0] = *(const LAS bf16x8*)(kb + 8192 + koff[d0]); }
;         ATT_SB();
; #pragma unroll
;         for (int d0 = 0; d0 < 8; ++d0) {
;             p[0] = __builtin_amdgcn_mfma_f32_32x32x16_bf16(ka[d0], qf[d0], p[0], 0, 0, 0);
;             p[1] = __builtin_amdgcn_mfma_f32_32x32x16_bf16(kc[d0], qf[d0], p[1], 0, 0, 0);
;         }
;     }
;     ATT_SB();
;     const bool need_mask = (k0 + 63 >= qw0);
;     float L[8], T[8];
;     ATT_PV(0); ATT_EXP8(0); ATT_SB();
;     ATT_PV(1); ATT_EXP8(1); ATT_SB();
;     ATT_PV(2); ATT_EXP8(2); ATT_SB();
;     ATT_PV(3); ATT_EXP8(3); ATT_SB();
;     if (need_mask) {
; #pragma unroll
;         for (int ph = 0; ph < 2; ++ph)
; #pragma unroll
;             for (int r = 0; r < 16; ++r) { const int key = k0 + 32 * ph + crow(r, hi); if (key >= qabs) p[ph][r] = 0.f; }
;     }
;     ATT_SB();
;     ATT_PV(4); ATT_LBLK(0); ATT_LBLK(1); ATT_SB();
;     ATT_PV(5); ATT_LBLK(2); ATT_LBLK(3); ATT_SB();
;     ATT_PV(6); ATT_LBLK(4); ATT_LBLK(5); ATT_SB();
;     ATT_PV(7); ATT_LBLK(6); ATT_LBLK(7); ATT_SB();
;     float run = carry;
;     ATT_PV(8); ATT_XCH(0); ATT_XCH(1); ATT_SB();
;     ATT_PV(9); ATT_XCH(2); ATT_XCH(3); ATT_SB();
;     ATT_PV(10); ATT_XCH(4); ATT_XCH(5); ATT_SB();
;     ATT_PV(11); ATT_XCH(6); ATT_XCH(7); ATT_SB();
;     carry = run;
;     ATT_PV(12); ATT_WGT(0); ATT_WGT(1); ATT_SB();
;     ATT_PV(13); ATT_WGT(2); ATT_WGT(3); ATT_SB();
;     ATT_PV(14); ATT_WGT(4); ATT_WGT(5); ATT_SB();
;     ATT_PV(15); ATT_WGT(6); ATT_WGT(7); ATT_SB();
; #pragma unroll
;     for (int s = 0; s < 4; ++s) { const int ph = s >> 1, rb = 8 * (s & 1);
;         u32x4 w; w.x = pk_bf16(p[ph][rb], p[ph][rb + 1]); w.y = pk_bf16(p[ph][rb + 2], p[ph][rb + 3]); w.z = pk_bf16(p[ph][rb + 4], p[ph][rb + 5]); w.w = pk_bf16(p[ph][rb + 6], p[ph][rb + 7]);
;         pa[s] = __builtin_bit_cast(bf16x8, w); }
	v_mfma_f32_32x32x16_bf16 v[16:31], v[140:143], v[64:67], v[16:31]
	v_mul_f32_e32 v64, v198, v199
	v_mul_f32_e32 v141, v76, v64
	v_mul_f32_e32 v64, v196, v64
	v_mul_f32_e32 v142, v77, v64
	v_mul_f32_e32 v64, v197, v64
	v_mul_f32_e32 v143, v75, v64
	v_add_f32_e32 v64, v201, v228
	v_exp_f32_e64 v64, -v64
	v_add_f32_e32 v65, v205, v229
	v_exp_f32_e64 v65, -v65
	v_mul_f32_e32 v140, v74, v199
	v_mul_f32_e32 v76, v72, v64
	v_mul_f32_e32 v64, v200, v64
	v_mul_f32_e32 v77, v176, v64
	v_mul_f32_e32 v64, v86, v64
	v_mul_f32_e32 v86, v177, v64
	v_mul_f32_e32 v64, v87, v64
	v_mul_f32_e32 v87, v73, v64
	v_add_f32_e32 v64, v209, v230
	v_mul_f32_e32 v74, v172, v65
	v_mul_f32_e32 v65, v204, v65
	v_mfma_f32_32x32x16_bf16 v[16:31], v[136:139], v[68:71], v[16:31]
	v_mul_f32_e32 v75, v174, v65
	v_mul_f32_e32 v65, v202, v65
	v_exp_f32_e64 v64, -v64
	v_mul_f32_e32 v136, v175, v65
	v_mul_f32_e32 v65, v203, v65
	v_mul_f32_e32 v137, v173, v65
	v_add_f32_e32 v65, v213, v231
	v_exp_f32_e64 v65, -v65
	v_mov_b32_e32 v159, v149
	v_mov_b32_e32 v194, v149
	v_mul_f32_e32 v72, v94, v64
	v_mul_f32_e32 v64, v208, v64
	v_permlane32_swap_b32_e32 v159, v194
	v_mul_f32_e32 v73, v170, v64
	v_mul_f32_e32 v64, v206, v64
	v_add_f32_e32 v66, v217, v232
	v_mul_f32_e32 v94, v171, v64
	v_mul_f32_e32 v64, v207, v64
	v_cndmask_b32_e64 v225, 0, v194, s[0:1]
	v_mul_f32_e32 v95, v95, v64
	v_mul_f32_e32 v70, v90, v65
	v_mul_f32_e32 v64, v212, v65
	v_exp_f32_e64 v65, -v66
	v_mfma_f32_32x32x16_bf16 v[16:31], v[132:135], v[78:81], v[16:31]
	v_add_f32_e32 v225, v158, v225
	v_add_f32_e32 v226, v159, v194
	v_mov_b32_e32 v159, v221
	v_mul_f32_e32 v71, v92, v64
	v_mul_f32_e32 v64, v210, v64
	v_permlane32_swap_b32_e32 v159, v227
	v_add_f32_e32 v67, v149, v225
	v_mul_f32_e32 v78, v93, v64
	v_mul_f32_e32 v64, v211, v64
	v_mul_f32_e32 v79, v91, v64
	v_mul_f32_e32 v68, v88, v65
	v_mul_f32_e32 v64, v216, v65
	v_exp_f32_e64 v65, -v67
	v_cndmask_b32_e64 v194, 0, v227, s[0:1]
	v_pk_add_f32 v[158:159], v[158:159], v[226:227]
	v_mul_f32_e32 v69, v168, v64
	v_mul_f32_e32 v64, v214, v64
	v_add_f32_e32 v194, v158, v194
	v_mul_f32_e32 v80, v169, v64
	v_mul_f32_e32 v64, v215, v64
	v_mul_f32_e32 v81, v89, v64
	v_mul_f32_e32 v66, v164, v65
	v_mul_f32_e32 v64, v220, v65
	v_add_f32_e32 v65, v221, v194
	v_mfma_f32_32x32x16_bf16 v[16:31], v[128:131], v[82:85], v[16:31]
	v_exp_f32_e64 v65, -v65
	v_mul_f32_e32 v67, v166, v64
	v_mul_f32_e32 v64, v218, v64
	v_mul_f32_e32 v82, v167, v64
	v_mul_f32_e32 v64, v219, v64
	v_mul_f32_e32 v83, v165, v64
	v_mul_f32_e32 v64, v160, v65
	v_mul_f32_e32 v65, v224, v65
	v_mul_f32_e32 v84, v162, v65
	v_mul_f32_e32 v65, v222, v65
	v_mul_f32_e32 v85, v163, v65
	v_mul_f32_e32 v65, v223, v65
	v_add_f32_e32 v159, v158, v159
	v_mul_f32_e32 v65, v161, v65
	v_cvt_pk_bf16_f32 v64, v64, v84
	v_cvt_pk_bf16_f32 v65, v85, v65
	v_cvt_pk_bf16_f32 v66, v66, v67
	v_cvt_pk_bf16_f32 v67, v82, v83
	v_cvt_pk_bf16_f32 v68, v68, v69
	v_cvt_pk_bf16_f32 v69, v80, v81
	v_cvt_pk_bf16_f32 v70, v70, v71
	v_cvt_pk_bf16_f32 v71, v78, v79
	v_cvt_pk_bf16_f32 v72, v72, v73
	v_cvt_pk_bf16_f32 v73, v94, v95
	v_cvt_pk_bf16_f32 v74, v74, v75
	v_cvt_pk_bf16_f32 v75, v136, v137
	v_cvt_pk_bf16_f32 v76, v76, v77
	v_cvt_pk_bf16_f32 v77, v86, v87
	v_cvt_pk_bf16_f32 v78, v140, v141
	v_cvt_pk_bf16_f32 v79, v142, v143

; #define LAS __attribute__((address_space(3)))
; __device__ __forceinline__ int crow(int r, int hi) { return (r & 3) + 8 * (r >> 2) + 4 * hi; }
; #define ATT_SB() do {} while (0)
; #define ATT_SB() do {} while (0)
; #define ATT_SB() __builtin_amdgcn_sched_barrier(0)
; #define ATT_VLD(f) do { const int c_ = (f) >> 2, s_ = (f) & 3; const s16x4 lo_ = vtr(vbp + 4096 * s_ + vbase[0] + vcq[c_]); const s16x4 hh_ = vtr(vbp + 4096 * s_ + vbase[1] + vcq[c_]); \
;         vf[f] = (bf16x8){lo_[0], lo_[1], lo_[2], lo_[3], hh_[0], hh_[1], hh_[2], hh_[3]}; } while (0)
; #define ATT_PV(f) do { if (DO_PV) { o[(f) >> 2] = __builtin_amdgcn_mfma_f32_32x32x16_bf16(pa[(f) & 3], vf[f], o[(f) >> 2], 0, 0, 0); if ((f) + 4 < 16) ATT_VLD((f) + 4); } } while (0)
; template <bool DO_PV> ...
;     f32x16 p[2];
; #pragma unroll
;     for (int r = 0; r < 16; ++r) { p[0][r] = 0.f; p[1][r] = 0.f; }
;     bf16x8 vf[16];
;     if (DO_PV) { ATT_VLD(0); ATT_VLD(1); ATT_VLD(2); ATT_VLD(3); }
;     {
;         bf16x8 ka[8], kc[8];
; #pragma unroll
;         for (int d0 = 0; d0 < 8; ++d0) { ka[d0] = *(const LAS bf16x8*)(kb + koff[d0]); kc[d0] = *(const LAS bf16x8*)(kb + 8192 + koff[d0]); }
;         ATT_SB();
; #pragma unroll
;         for (int d0 = 0; d0 < 8; ++d0) {
;             p[0] = __builtin_amdgcn_mfma_f32_32x32x16_bf16(ka[d0], qf[d0], p[0], 0, 0, 0);
;             p[1] = __builtin_amdgcn_mfma_f32_32x32x16_bf16(kc[d0], qf[d0], p[1], 0, 0, 0);
;         }
;     }
;     ATT_SB();
;     const bool need_mask = (k0 + 63 >= qw0);
;     float L[8], T[8];
;     ATT_PV(0); ATT_EXP8(0); ATT_SB();
;     ATT_PV(1); ATT_EXP8(1); ATT_SB();
;     ATT_PV(2); ATT_EXP8(2); ATT_SB();
;     ATT_PV(3); ATT_EXP8(3); ATT_SB();
;     if (need_mask) {
; #pragma unroll
;         for (int ph = 0; ph < 2; ++ph)
; #pragma unroll
;             for (int r = 0; r < 16; ++r) { const int key = k0 + 32 * ph + crow(r, hi); if (key >= qabs) p[ph][r] = 0.f; }
;     }
;     ATT_SB();
;     ATT_PV(4); ATT_LBLK(0); ATT_LBLK(1); ATT_SB();
;     ATT_PV(5); ATT_LBLK(2); ATT_LBLK(3); ATT_SB();
;     ATT_PV(6); ATT_LBLK(4); ATT_LBLK(5); ATT_SB();
;     ATT_PV(7); ATT_LBLK(6); ATT_LBLK(7); ATT_SB();
;     float run = carry;
;     ATT_PV(8); ATT_XCH(0); ATT_XCH(1); ATT_SB();
;     ATT_PV(9); ATT_XCH(2); ATT_XCH(3); ATT_SB();
;     ATT_PV(10); ATT_XCH(4); ATT_XCH(5); ATT_SB();
;     ATT_PV(11); ATT_XCH(6); ATT_XCH(7); ATT_SB();
.LBB0_623:
	s_waitcnt lgkmcnt(0)
	v_mfma_f32_32x32x16_bf16 v[48:63], v[140:143], v[84:87], v[48:63]
	v_add_f32_e64 v196, v76, 1.0
	v_add_f32_e64 v197, v77, 1.0
	v_add_f32_e64 v198, v74, 1.0
	v_add_f32_e64 v199, v75, 1.0
	v_add_f32_e64 v86, v176, 1.0
	v_add_f32_e64 v87, v177, 1.0
	v_pk_mul_f32 v[78:79], v[196:197], v[198:199]
	v_pk_add_f32 v[200:201], v[72:73], 1.0 op_sel_hi:[1,0]
	v_mul_f32_e32 v78, v78, v79
	v_log_f32_e32 v199, v78
	v_mfma_f32_32x32x16_bf16 v[48:63], v[136:139], v[80:83], v[48:63]
	v_mul_f32_e64 v78, v86, v200
	v_mul_f32_e64 v79, v87, v201
	v_add_f32_e64 v202, v174, 1.0
	v_add_f32_e64 v203, v175, 1.0
	v_mul_f32_e32 v78, v78, v79
	v_pk_add_f32 v[204:205], v[172:173], 1.0 op_sel_hi:[1,0]
	v_pk_add_f32 v[210:211], v[92:93], 1.0 op_sel_hi:[1,0]
	v_pk_add_f32 v[212:213], v[90:91], 1.0 op_sel_hi:[1,0]
	v_log_f32_e32 v201, v78
	v_mfma_f32_32x32x16_bf16 v[48:63], v[132:135], v[68:71], v[48:63]
	v_mul_f32_e64 v78, v202, v204
	v_mul_f32_e64 v79, v203, v205
	v_mul_f32_e64 v68, v210, v212
	v_mul_f32_e64 v69, v211, v213
	v_mul_f32_e32 v78, v78, v79
	v_pk_add_f32 v[206:207], v[170:171], 1.0 op_sel_hi:[1,0]
	v_pk_add_f32 v[208:209], v[94:95], 1.0 op_sel_hi:[1,0]
	v_mul_f32_e32 v68, v68, v69
	v_pk_add_f32 v[214:215], v[168:169], 1.0 op_sel_hi:[1,0]
	v_pk_add_f32 v[216:217], v[88:89], 1.0 op_sel_hi:[1,0]
	v_log_f32_e32 v205, v78
	v_pk_mul_f32 v[78:79], v[206:207], v[208:209]
	v_log_f32_e32 v213, v68
	v_pk_mul_f32 v[68:69], v[214:215], v[216:217]
	v_add_u32_e32 v149, v159, v192
	v_mul_f32_e32 v78, v78, v79
	v_mul_f32_e32 v68, v68, v69
	v_add_u32_e32 v218, v194, v192
	v_log_f32_e32 v209, v78
	v_log_f32_e32 v217, v68
	v_mfma_f32_32x32x16_bf16 v[48:63], v[128:131], v[64:67], v[48:63]
	ds_read_b64_tr_b16 v[64:65], v149 offset:32768
	ds_read_b64_tr_b16 v[68:69], v149 offset:36864
	ds_read_b64_tr_b16 v[78:79], v149 offset:40960
	ds_read_b64_tr_b16 v[82:83], v149 offset:45056
	ds_read_b64_tr_b16 v[66:67], v218 offset:34816
	ds_read_b64_tr_b16 v[70:71], v218 offset:38912
	ds_read_b64_tr_b16 v[80:81], v218 offset:43008
	ds_read_b64_tr_b16 v[84:85], v218 offset:47104
	v_pk_add_f32 v[218:219], v[166:167], 1.0 op_sel_hi:[1,0]
	v_pk_add_f32 v[220:221], v[164:165], 1.0 op_sel_hi:[1,0]
	v_pk_add_f32 v[224:225], v[160:161], 1.0 op_sel_hi:[1,0]
	v_pk_mul_f32 v[222:223], v[218:219], v[220:221]
	v_add_u32_e32 v194, v194, v193
	v_mul_f32_e32 v149, v222, v223
	s_waitcnt lgkmcnt(0)
	v_mfma_f32_32x32x16_bf16 v[0:15], v[140:143], v[64:67], v[0:15]
	v_mov_b32_e32 v64, v199
	v_mov_b32_e32 v65, v199
	s_nop 1
	v_permlane32_swap_b32_e32 v64, v65
	v_add_f32_e64 v222, v162, 1.0
	v_add_f32_e64 v223, v163, 1.0
	v_pk_mul_f32 v[226:227], v[222:223], v[224:225]
	v_add_u32_e32 v225, v159, v193
	v_cndmask_b32_e64 v66, 0, v65, s[0:1]
	v_add_f32_e32 v64, v64, v65
	v_mov_b32_e32 v159, v201
	v_mov_b32_e32 v65, v201
	s_nop 1
	v_permlane32_swap_b32_e32 v159, v65
	v_add_f32_e32 v66, v158, v66
	v_add_f32_e32 v199, v199, v66
	v_mfma_f32_32x32x16_bf16 v[0:15], v[136:139], v[68:71], v[0:15]
	v_cndmask_b32_e64 v66, 0, v65, s[0:1]
	v_add_f32_e64 v64, v158, v64
	v_add_f32_e64 v65, v159, v65
	v_exp_f32_e64 v199, -v199
	v_add_f32_e32 v228, v64, v66
	v_pk_add_f32 v[64:65], v[64:65], v[64:65] op_sel:[0,1] op_sel_hi:[1,0]
	v_mov_b32_e32 v66, v205
	v_mov_b32_e32 v65, v205
	s_nop 1
	v_permlane32_swap_b32_e32 v65, v66
	v_mfma_f32_32x32x16_bf16 v[0:15], v[132:135], v[78:81], v[0:15]
	v_log_f32_e32 v149, v149
	v_cndmask_b32_e64 v67, 0, v66, s[0:1]
	v_add_f32_e32 v229, v64, v67
	v_add_f32_e32 v66, v65, v66
	v_mov_b32_e32 v65, v209
	v_mov_b32_e32 v67, v209
	s_nop 1
	v_permlane32_swap_b32_e32 v65, v67
	v_mfma_f32_32x32x16_bf16 v[0:15], v[128:131], v[82:85], v[0:15]
	v_mul_f32_e32 v221, v226, v227
	v_cndmask_b32_e64 v68, 0, v67, s[0:1]
	v_add_f32_e64 v64, v64, v66
	v_add_f32_e64 v65, v65, v67
	v_mov_b32_e32 v66, v213
	v_add_f32_e32 v230, v64, v68
	v_pk_add_f32 v[64:65], v[64:65], v[64:65] op_sel:[0,1] op_sel_hi:[1,0]
	v_log_f32_e32 v221, v221
	v_mov_b32_e32 v65, v213
	s_nop 1
	v_permlane32_swap_b32_e32 v65, v66
	v_mov_b32_e32 v227, v221
	s_nop 0
	v_cndmask_b32_e64 v67, 0, v66, s[0:1]
	v_add_f32_e32 v231, v64, v67
	v_add_f32_e32 v66, v65, v66
	v_mov_b32_e32 v65, v217
	v_mov_b32_e32 v67, v217
	s_nop 1
	v_permlane32_swap_b32_e32 v65, v67
	s_nop 1
	v_cndmask_b32_e64 v68, 0, v67, s[0:1]
	v_pk_add_f32 v[64:65], v[64:65], v[66:67]
	s_nop 0
	v_add_f32_e32 v232, v64, v68
	v_pk_add_f32 v[158:159], v[64:65], v[64:65] op_sel:[0,1] op_sel_hi:[1,0]
	ds_read_b64_tr_b16 v[64:65], v225 offset:32768
	ds_read_b64_tr_b16 v[68:69], v225 offset:36864
	ds_read_b64_tr_b16 v[78:79], v225 offset:40960
	ds_read_b64_tr_b16 v[82:83], v225 offset:45056
	ds_read_b64_tr_b16 v[66:67], v194 offset:34816
	ds_read_b64_tr_b16 v[70:71], v194 offset:38912
	ds_read_b64_tr_b16 v[80:81], v194 offset:43008
	ds_read_b64_tr_b16 v[84:85], v194 offset:47104
	s_waitcnt lgkmcnt(0)
; #define LAS __attribute__((address_space(3)))
; __device__ __forceinline__ unsigned pk_bf16(float lo, float hi) { return pg8::cvt_pk_bf16(lo, hi); }
; #define ATT_SB() do {} while (0)
; template <bool DO_PV> ...
;     f32x16 p[2];
; #pragma unroll
;     for (int r = 0; r < 16; ++r) { p[0][r] = 0.f; p[1][r] = 0.f; }
;     bf16x8 vf[16];
;     if (DO_PV) { ATT_VLD(0); ATT_VLD(1); ATT_VLD(2); ATT_VLD(3); }
;     {
;         bf16x8 ka[8], kc[8];
; #pragma unroll
;         for (int d0 = 0; d0 < 8; ++d0) { ka[d0] = *(const LAS bf16x8*)(kb + koff[d0]); kc[d0] = *(const LAS bf16x8*)(kb + 8192 + koff[d0]); }
;         ATT_SB();
; #pragma unroll
;         for (int d0 = 0; d0 < 8; ++d0) {
;             p[0] = __builtin_amdgcn_mfma_f32_32x32x16_bf16(ka[d0], qf[d0], p[0], 0, 0, 0);
;             p[1] = __builtin_amdgcn_mfma_f32_32x32x16_bf16(kc[d0], qf[d0], p[1], 0, 0, 0);
;         }
;     }
;     ATT_SB();
;     const bool need_mask = (k0 + 63 >= qw0);
;     float L[8], T[8];
;     ATT_PV(0); ATT_EXP8(0); ATT_SB();
;     ATT_PV(1); ATT_EXP8(1); ATT_SB();
;     ATT_PV(2); ATT_EXP8(2); ATT_SB();
;     ATT_PV(3); ATT_EXP8(3); ATT_SB();
;     if (need_mask) {
; #pragma unroll
;         for (int ph = 0; ph < 2; ++ph)
; #pragma unroll
;             for (int r = 0; r < 16; ++r) { const int key = k0 + 32 * ph + crow(r, hi); if (key >= qabs) p[ph][r] = 0.f; }
;     }
;     ATT_SB();
;     ATT_PV(4); ATT_LBLK(0); ATT_LBLK(1); ATT_SB();
;     ATT_PV(5); ATT_LBLK(2); ATT_LBLK(3); ATT_SB();
;     ATT_PV(6); ATT_LBLK(4); ATT_LBLK(5); ATT_SB();
;     ATT_PV(7); ATT_LBLK(6); ATT_LBLK(7); ATT_SB();
;     float run = carry;
;     ATT_PV(8); ATT_XCH(0); ATT_XCH(1); ATT_SB();
;     ATT_PV(9); ATT_XCH(2); ATT_XCH(3); ATT_SB();
;     ATT_PV(10); ATT_XCH(4); ATT_XCH(5); ATT_SB();
;     ATT_PV(11); ATT_XCH(6); ATT_XCH(7); ATT_SB();
;     carry = run;
;     ATT_PV(12); ATT_WGT(0); ATT_WGT(1); ATT_SB();
;     ATT_PV(13); ATT_WGT(2); ATT_WGT(3); ATT_SB();
;     ATT_PV(14); ATT_WGT(4); ATT_WGT(5); ATT_SB();
;     ATT_PV(15); ATT_WGT(6); ATT_WGT(7); ATT_SB();
; #pragma unroll
;     for (int s = 0; s < 4; ++s) { const int ph = s >> 1, rb = 8 * (s & 1);
;         u32x4 w; w.x = pk_bf16(p[ph][rb], p[ph][rb + 1]); w.y = pk_bf16(p[ph][rb + 2], p[ph][rb + 3]); w.z = pk_bf16(p[ph][rb + 4], p[ph][rb + 5]); w.w = pk_bf16(p[ph][rb + 6], p[ph][rb + 7]);
;         pa[s] = __builtin_bit_cast(bf16x8, w); }
	v_mfma_f32_32x32x16_bf16 v[16:31], v[140:143], v[64:67], v[16:31]
	v_mul_f32_e32 v64, v198, v199
	v_mul_f32_e32 v141, v76, v64
	v_mul_f32_e32 v64, v196, v64
	v_mul_f32_e32 v142, v77, v64
	v_mul_f32_e32 v64, v197, v64
	v_mul_f32_e32 v143, v75, v64
	v_add_f32_e32 v64, v201, v228
	v_exp_f32_e64 v64, -v64
	v_add_f32_e32 v65, v205, v229
	v_exp_f32_e64 v65, -v65
	v_mul_f32_e32 v140, v74, v199
	v_mul_f32_e32 v76, v72, v64
	v_mul_f32_e32 v64, v200, v64
	v_mul_f32_e32 v77, v176, v64
	v_mul_f32_e32 v64, v86, v64
	v_mul_f32_e32 v86, v177, v64
	v_mul_f32_e32 v64, v87, v64
	v_mul_f32_e32 v87, v73, v64
	v_add_f32_e32 v64, v209, v230
	v_mul_f32_e32 v74, v172, v65
	v_mul_f32_e32 v65, v204, v65
	v_mfma_f32_32x32x16_bf16 v[16:31], v[136:139], v[68:71], v[16:31]
	v_mul_f32_e32 v75, v174, v65
	v_mul_f32_e32 v65, v202, v65
	v_exp_f32_e64 v64, -v64
	v_mul_f32_e32 v136, v175, v65
	v_mul_f32_e32 v65, v203, v65
	v_mul_f32_e32 v137, v173, v65
	v_add_f32_e32 v65, v213, v231
	v_exp_f32_e64 v65, -v65
	v_mov_b32_e32 v159, v149
	v_mov_b32_e32 v194, v149
	v_mul_f32_e32 v72, v94, v64
	v_mul_f32_e32 v64, v208, v64
	v_permlane32_swap_b32_e32 v159, v194
	v_mul_f32_e32 v73, v170, v64
	v_mul_f32_e32 v64, v206, v64
	v_add_f32_e32 v66, v217, v232
	v_mul_f32_e32 v94, v171, v64
	v_mul_f32_e32 v64, v207, v64
	v_cndmask_b32_e64 v225, 0, v194, s[0:1]
	v_mul_f32_e32 v95, v95, v64
	v_mul_f32_e32 v70, v90, v65
	v_mul_f32_e32 v64, v212, v65
	v_exp_f32_e64 v65, -v66
	v_mfma_f32_32x32x16_bf16 v[16:31], v[132:135], v[78:81], v[16:31]
	v_add_f32_e32 v225, v158, v225
	v_add_f32_e32 v226, v159, v194
	v_mov_b32_e32 v159, v221
	v_mul_f32_e32 v71, v92, v64
	v_mul_f32_e32 v64, v210, v64
	v_permlane32_swap_b32_e32 v159, v227
	v_add_f32_e32 v67, v149, v225
	v_mul_f32_e32 v78, v93, v64
	v_mul_f32_e32 v64, v211, v64
	v_mul_f32_e32 v79, v91, v64
	v_mul_f32_e32 v68, v88, v65
	v_mul_f32_e32 v64, v216, v65
	v_exp_f32_e64 v65, -v67
	v_cndmask_b32_e64 v194, 0, v227, s[0:1]
	v_pk_add_f32 v[158:159], v[158:159], v[226:227]
	v_mul_f32_e32 v69, v168, v64
	v_mul_f32_e32 v64, v214, v64
	v_add_f32_e32 v194, v158, v194
	v_mul_f32_e32 v80, v169, v64
	v_mul_f32_e32 v64, v215, v64
	v_mul_f32_e32 v81, v89, v64
	v_mul_f32_e32 v66, v164, v65
	v_mul_f32_e32 v64, v220, v65
	v_add_f32_e32 v65, v221, v194
	v_mfma_f32_32x32x16_bf16 v[16:31], v[128:131], v[82:85], v[16:31]
	v_exp_f32_e64 v65, -v65
	v_mul_f32_e32 v67, v166, v64
	v_mul_f32_e32 v64, v218, v64
	v_mul_f32_e32 v82, v167, v64
	v_mul_f32_e32 v64, v219, v64
	v_mul_f32_e32 v83, v165, v64
	v_mul_f32_e32 v64, v160, v65
	v_mul_f32_e32 v65, v224, v65
	v_mul_f32_e32 v84, v162, v65
	v_mul_f32_e32 v65, v222, v65
	v_mul_f32_e32 v85, v163, v65
	v_mul_f32_e32 v65, v223, v65
	v_add_f32_e32 v159, v158, v159
	v_mul_f32_e32 v65, v161, v65
	v_cvt_pk_bf16_f32 v64, v64, v84
	v_cvt_pk_bf16_f32 v65, v85, v65
	v_cvt_pk_bf16_f32 v66, v66, v67
	v_cvt_pk_bf16_f32 v67, v82, v83
	v_cvt_pk_bf16_f32 v68, v68, v69
	v_cvt_pk_bf16_f32 v69, v80, v81
	v_cvt_pk_bf16_f32 v70, v70, v71
	v_cvt_pk_bf16_f32 v71, v78, v79
	v_cvt_pk_bf16_f32 v72, v72, v73
	v_cvt_pk_bf16_f32 v73, v94, v95
	v_cvt_pk_bf16_f32 v74, v74, v75
	v_cvt_pk_bf16_f32 v75, v136, v137
	v_cvt_pk_bf16_f32 v76, v76, v77
	v_cvt_pk_bf16_f32 v77, v86, v87
	v_cvt_pk_bf16_f32 v78, v140, v141
	v_cvt_pk_bf16_f32 v79, v142, v143
